# v38_attnshift
# baseline (speedup 1.0000x reference)
; DEVI float sxor(float v, int mask, int lane) { return __int_as_float(__builtin_amdgcn_ds_bpermute((lane ^ mask) << 2, __float_as_int(v))); }
; DEVI void attn_phase(int wv, const Params& p, char* smem) {
;     ...
;           if (__builtin_amdgcn_ballot_w64(mx > mrun[nt] + 8.f) != 0ull) {
;             mx = fmaxf(mx, sxor(mx, 16, lane));
;             mx = fmaxf(mx, sxor(mx, 32, lane));
;             const float mnew = mx > mrun[nt] + 8.f ? mx : mrun[nt];
;             const float alpha = __builtin_amdgcn_exp2f(mrun[nt] - mnew);
;             lrun[nt] *= alpha;
; #pragma unroll
;             for (int dt = 0; dt < 8; ++dt) ot[dt][nt] *= alpha;
;             mrun[nt] = mnew;
;           }
;           const float mref = mrun[nt];
;           float ps = 0.f;
; #pragma unroll
;           for (int mh = 0; mh < 2; ++mh)
; #pragma unroll
;             for (int j = 0; j < 4; ++j) {
;               const float pv = __builtin_amdgcn_exp2f(st[2 * kk + mh][nt][j] - mref);
;     ...
;       asm volatile("s_waitcnt vmcnt(0)" ::: "memory");
;       __syncthreads();
;     }
.Lattn_f_end:
	s_add_i32 s15, s15, 1
	s_add_i32 s19, s19, 64
	s_waitcnt vmcnt(0) lgkmcnt(0)
	s_barrier
	s_cmp_eq_u32 s18, s15
	s_cbranch_scc1 .LBB0_986
	v_sub_f32_e32 v184, 0, v181
	v_sub_f32_e32 v185, 0, v181
	v_sub_f32_e32 v186, 0, v181
	v_sub_f32_e32 v187, 0, v181
	v_sub_f32_e32 v188, 0, v180
	v_sub_f32_e32 v189, 0, v180
	v_sub_f32_e32 v190, 0, v180
	v_sub_f32_e32 v191, 0, v180
	v_mov_b32_e32 v253, 0x41000000
	.p2align	6
	s_nop 0
